# stagger step halved (0..2.4us)
# speedup vs baseline: 1.1111x; 1.0002x over previous
.Lstg_loop:
	s_cmp_eq_u32 s2, 0
	s_cbranch_scc1 .Lstg_skip
	s_sleep 12
	s_sub_u32 s2, s2, 1
	s_branch .Lstg_loop
